# v9 plus attn_merge loop processing two elements per iteration (12 loads in flight per lane)
# baseline (speedup 1.0000x reference)
.LBB0_1080:
	s_cmp_lt_i32 s94, 7
	s_cselect_b64 s[4:5], -1, 0
	s_add_u32 s8, s14, 0x59e00000
	s_addc_u32 s9, s15, 0
	s_add_u32 s10, s14, 0x5de00000
	s_addc_u32 s11, s15, 0
	s_and_b64 s[16:17], s[4:5], s[0:1]
	s_andn2_b64 vcc, exec, s[16:17]
	s_cbranch_vccnz .LBB0_1110
	v_readlane_b32 s0, v222, 2
	s_nop 1
	v_lshl_or_b32 v1, s0, 9, v0
	s_mov_b32 s0, 0x200000
	s_nop 0
	v_cmp_gt_i32_e32 vcc, s0, v1
	s_and_saveexec_b64 s[0:1], vcc
	s_cbranch_execz .LBB0_1084
	s_add_u32 s4, s14, 0x32600000
	s_addc_u32 s5, s15, 0
	s_lshl_b32 s3, s13, 9
	v_lshlrev_b32_e32 v4, 3, v1
	s_lshl_b32 s24, s13, 12
	s_mov_b64 s[6:7], 0
	v_mov_b32_e32 v3, 0
	v_mov_b32_e32 v43, 0
	s_mov_b64 s[18:19], 0x4000
	s_mov_b64 s[20:21], 0x8000
	s_mov_b32 s25, 0x1fffff
.LBB0_1083:
	v_ashrrev_i32_e32 v6, 7, v1
	v_ashrrev_i32_e32 v7, 31, v6
	v_lshrrev_b32_e32 v2, 5, v4
	v_lshlrev_b64 v[8:9], 5, v[6:7]
	v_lshl_add_u64 v[10:11], v[6:7], 0, s[18:19]
	v_lshl_add_u64 v[12:13], v[6:7], 0, s[20:21]
	v_and_b32_e32 v2, 28, v2
	v_lshl_add_u64 v[8:9], s[4:5], 0, v[8:9]
	v_lshlrev_b64 v[14:15], 5, v[10:11]
	v_lshlrev_b64 v[16:17], 5, v[12:13]
	v_and_b32_e32 v5, 0x3f8, v4
	v_lshlrev_b64 v[6:7], 11, v[6:7]
	v_lshlrev_b64 v[10:11], 11, v[10:11]
	v_lshlrev_b64 v[12:13], 11, v[12:13]
	v_lshl_add_u64 v[8:9], v[8:9], 0, v[2:3]
	v_lshl_add_u64 v[14:15], s[4:5], 0, v[14:15]
	v_lshl_add_u64 v[16:17], s[4:5], 0, v[16:17]
	v_lshl_add_u64 v[18:19], s[38:39], 0, v[6:7]
	v_lshl_add_u64 v[10:11], s[38:39], 0, v[10:11]
	v_lshl_add_u64 v[12:13], s[38:39], 0, v[12:13]
	v_lshl_add_u64 v[14:15], v[14:15], 0, v[2:3]
	v_lshl_add_u64 v[16:17], v[16:17], 0, v[2:3]
	v_lshlrev_b32_e32 v2, 1, v5
	global_load_dword v5, v[8:9], off
	global_load_dword v20, v[14:15], off
	global_load_dword v21, v[16:17], off
	v_lshl_add_u64 v[6:7], s[8:9], 0, v[6:7]
	v_lshl_add_u64 v[14:15], v[18:19], 0, v[2:3]
	v_lshl_add_u64 v[8:9], v[10:11], 0, v[2:3]
	v_lshl_add_u64 v[16:17], v[12:13], 0, v[2:3]
	v_lshl_add_u64 v[18:19], v[6:7], 0, v[2:3]
	global_load_dwordx4 v[6:9], v[8:9], off
	s_nop 0
	global_load_dwordx4 v[10:13], v[14:15], off
	s_nop 0
	global_load_dwordx4 v[14:17], v[16:17], off
	v_add_u32_e32 v1, s3, v1
	v_add_u32_e32 v4, s24, v4
	v_cmp_ge_i32_e32 vcc, s25, v1
	s_and_saveexec_b64 s[98:99], vcc
	v_ashrrev_i32_e32 v46, 7, v1
	v_ashrrev_i32_e32 v47, 31, v46
	v_lshrrev_b32_e32 v42, 5, v4
	v_lshlrev_b64 v[48:49], 5, v[46:47]
	v_lshl_add_u64 v[50:51], v[46:47], 0, s[18:19]
	v_lshl_add_u64 v[52:53], v[46:47], 0, s[20:21]
	v_and_b32_e32 v42, 28, v42
	v_lshl_add_u64 v[48:49], s[4:5], 0, v[48:49]
	v_lshlrev_b64 v[54:55], 5, v[50:51]
	v_lshlrev_b64 v[56:57], 5, v[52:53]
	v_and_b32_e32 v45, 0x3f8, v4
	v_lshlrev_b64 v[46:47], 11, v[46:47]
	v_lshlrev_b64 v[50:51], 11, v[50:51]
	v_lshlrev_b64 v[52:53], 11, v[52:53]
	v_lshl_add_u64 v[48:49], v[48:49], 0, v[42:43]
	v_lshl_add_u64 v[54:55], s[4:5], 0, v[54:55]
	v_lshl_add_u64 v[56:57], s[4:5], 0, v[56:57]
	v_lshl_add_u64 v[58:59], s[38:39], 0, v[46:47]
	v_lshl_add_u64 v[50:51], s[38:39], 0, v[50:51]
	v_lshl_add_u64 v[52:53], s[38:39], 0, v[52:53]
	v_lshl_add_u64 v[54:55], v[54:55], 0, v[42:43]
	v_lshl_add_u64 v[56:57], v[56:57], 0, v[42:43]
	v_lshlrev_b32_e32 v42, 1, v45
	global_load_dword v45, v[48:49], off
	global_load_dword v60, v[54:55], off
	global_load_dword v61, v[56:57], off
	v_lshl_add_u64 v[46:47], s[8:9], 0, v[46:47]
	v_lshl_add_u64 v[54:55], v[58:59], 0, v[42:43]
	v_lshl_add_u64 v[48:49], v[50:51], 0, v[42:43]
	v_lshl_add_u64 v[56:57], v[52:53], 0, v[42:43]
	v_lshl_add_u64 v[58:59], v[46:47], 0, v[42:43]
	global_load_dwordx4 v[46:49], v[48:49], off
	s_nop 0
	global_load_dwordx4 v[50:53], v[54:55], off
	s_nop 0
	global_load_dwordx4 v[54:57], v[56:57], off
	s_mov_b64 s[100:101], exec
	s_mov_b64 exec, s[98:99]
	v_add_u32_e32 v1, s3, v1
	v_cmp_lt_i32_e32 vcc, s25, v1
	s_or_b64 s[6:7], vcc, s[6:7]
	v_add_u32_e32 v4, s24, v4
	s_waitcnt vmcnt(9)
	v_max3_f32 v2, v5, v20, v21
	v_sub_f32_e32 v5, v5, v2
	v_sub_f32_e32 v28, v20, v2
	v_sub_f32_e32 v2, v21, v2
	s_waitcnt vmcnt(8)
	v_lshlrev_b32_e32 v31, 16, v7
	v_and_b32_e32 v32, 0xffff0000, v7
	s_waitcnt vmcnt(7)
	v_lshlrev_b32_e32 v7, 16, v10
	v_and_b32_e32 v21, 0xffff0000, v10
	s_waitcnt vmcnt(6)
	v_lshlrev_b32_e32 v22, 16, v15
	v_and_b32_e32 v10, 0xffff0000, v15
	v_lshlrev_b32_e32 v15, 16, v12
	v_and_b32_e32 v25, 0xffff0000, v12
	v_mul_f32_e32 v5, 0x3fb8aa3b, v5
	v_mul_f32_e32 v12, 0x3fb8aa3b, v28
	v_lshlrev_b32_e32 v35, 16, v9
	v_lshlrev_b32_e32 v27, 16, v13
	v_and_b32_e32 v36, 0xffff0000, v9
	v_and_b32_e32 v9, 0xffff0000, v13
	v_mul_f32_e32 v2, 0x3fb8aa3b, v2
	v_exp_f32_e32 v13, v5
	v_exp_f32_e32 v5, v12
	v_exp_f32_e32 v12, v2
	v_lshlrev_b32_e32 v29, 16, v6
	v_and_b32_e32 v30, 0xffff0000, v6
	v_add_f32_e32 v2, v13, v5
	v_add_f32_e32 v2, v12, v2
	v_lshlrev_b32_e32 v6, 16, v14
	v_and_b32_e32 v20, 0xffff0000, v14
	v_lshlrev_b32_e32 v14, 16, v16
	v_and_b32_e32 v24, 0xffff0000, v16
	v_div_scale_f32 v16, s[40:41], v2, v2, 1.0
	v_rcp_f32_e32 v28, v16
	v_lshlrev_b32_e32 v33, 16, v8
	v_and_b32_e32 v34, 0xffff0000, v8
	v_lshlrev_b32_e32 v26, 16, v17
	v_fma_f32 v37, -v16, v28, 1.0
	v_and_b32_e32 v8, 0xffff0000, v17
	v_div_scale_f32 v17, vcc, 1.0, v2, 1.0
	v_fmac_f32_e32 v28, v37, v28
	v_mul_f32_e32 v37, v17, v28
	v_fma_f32 v38, -v16, v37, v17
	v_fmac_f32_e32 v37, v38, v28
	v_fma_f32 v16, -v16, v37, v17
	v_div_fmas_f32 v16, v16, v28, v37
	v_div_fixup_f32 v2, v16, v2, 1.0
	v_lshlrev_b32_e32 v23, 16, v11
	v_and_b32_e32 v11, 0xffff0000, v11
	v_pk_mul_f32 v[12:13], v[12:13], v[2:3] op_sel_hi:[1,0]
	v_mul_f32_e32 v5, v5, v2
	v_pk_mul_f32 v[6:7], v[12:13], v[6:7]
	v_pk_mul_f32 v[16:17], v[12:13], v[20:21]
	v_pk_mul_f32 v[20:21], v[12:13], v[22:23]
	v_pk_mul_f32 v[10:11], v[12:13], v[10:11]
	v_pk_mul_f32 v[14:15], v[12:13], v[14:15]
	v_pk_mul_f32 v[22:23], v[12:13], v[24:25]
	v_pk_mul_f32 v[24:25], v[12:13], v[26:27]
	v_pk_mul_f32 v[8:9], v[12:13], v[8:9]
	v_fma_f32 v2, v5, v29, v7
	v_fma_f32 v7, v5, v30, v17
	v_fma_f32 v12, v5, v31, v21
	v_fma_f32 v11, v5, v32, v11
	v_fma_f32 v13, v5, v33, v15
	v_fma_f32 v15, v5, v34, v23
	v_fma_f32 v17, v5, v35, v25
	v_fma_f32 v5, v5, v36, v9
	v_add_f32_e32 v2, v6, v2
	v_add_f32_e32 v6, v16, v7
	v_add_f32_e32 v7, v20, v12
	v_add_f32_e32 v9, v10, v11
	v_add_f32_e32 v10, v14, v13
	v_add_f32_e32 v11, v22, v15
	v_add_f32_e32 v12, v24, v17
	v_add_f32_e32 v5, v8, v5
	v_cvt_pk_bf16_f32 v6, v2, v6
	v_cvt_pk_bf16_f32 v7, v7, v9
	v_cvt_pk_bf16_f32 v8, v10, v11
	v_cvt_pk_bf16_f32 v9, v12, v5
	global_store_dwordx4 v[18:19], v[6:9], off
	s_mov_b64 exec, s[100:101]
	s_waitcnt vmcnt(4)
	v_max3_f32 v42, v45, v60, v61
	v_sub_f32_e32 v45, v45, v42
	v_sub_f32_e32 v68, v60, v42
	v_sub_f32_e32 v42, v61, v42
	s_waitcnt vmcnt(3)
	v_lshlrev_b32_e32 v71, 16, v47
	v_and_b32_e32 v72, 0xffff0000, v47
	s_waitcnt vmcnt(2)
	v_lshlrev_b32_e32 v47, 16, v50
	v_and_b32_e32 v61, 0xffff0000, v50
	s_waitcnt vmcnt(1)
	v_lshlrev_b32_e32 v62, 16, v55
	v_and_b32_e32 v50, 0xffff0000, v55
	v_lshlrev_b32_e32 v55, 16, v52
	v_and_b32_e32 v65, 0xffff0000, v52
	v_mul_f32_e32 v45, 0x3fb8aa3b, v45
	v_mul_f32_e32 v52, 0x3fb8aa3b, v68
	v_lshlrev_b32_e32 v75, 16, v49
	v_lshlrev_b32_e32 v67, 16, v53
	v_and_b32_e32 v76, 0xffff0000, v49
	v_and_b32_e32 v49, 0xffff0000, v53
	v_mul_f32_e32 v42, 0x3fb8aa3b, v42
	v_exp_f32_e32 v53, v45
	v_exp_f32_e32 v45, v52
	v_exp_f32_e32 v52, v42
	v_lshlrev_b32_e32 v69, 16, v46
	v_and_b32_e32 v70, 0xffff0000, v46
	v_add_f32_e32 v42, v53, v45
	v_add_f32_e32 v42, v52, v42
	v_lshlrev_b32_e32 v46, 16, v54
	v_and_b32_e32 v60, 0xffff0000, v54
	v_lshlrev_b32_e32 v54, 16, v56
	v_and_b32_e32 v64, 0xffff0000, v56
	v_div_scale_f32 v56, s[40:41], v42, v42, 1.0
	v_rcp_f32_e32 v68, v56
	v_lshlrev_b32_e32 v73, 16, v48
	v_and_b32_e32 v74, 0xffff0000, v48
	v_lshlrev_b32_e32 v66, 16, v57
	v_fma_f32 v77, -v56, v68, 1.0
	v_and_b32_e32 v48, 0xffff0000, v57
	v_div_scale_f32 v57, vcc, 1.0, v42, 1.0
	v_fmac_f32_e32 v68, v77, v68
	v_mul_f32_e32 v77, v57, v68
	v_fma_f32 v78, -v56, v77, v57
	v_fmac_f32_e32 v77, v78, v68
	v_fma_f32 v56, -v56, v77, v57
	v_div_fmas_f32 v56, v56, v68, v77
	v_div_fixup_f32 v42, v56, v42, 1.0
	v_lshlrev_b32_e32 v63, 16, v51
	v_and_b32_e32 v51, 0xffff0000, v51
	v_pk_mul_f32 v[52:53], v[52:53], v[42:43] op_sel_hi:[1,0]
	v_mul_f32_e32 v45, v45, v42
	v_pk_mul_f32 v[46:47], v[52:53], v[46:47]
	v_pk_mul_f32 v[56:57], v[52:53], v[60:61]
	v_pk_mul_f32 v[60:61], v[52:53], v[62:63]
	v_pk_mul_f32 v[50:51], v[52:53], v[50:51]
	v_pk_mul_f32 v[54:55], v[52:53], v[54:55]
	v_pk_mul_f32 v[62:63], v[52:53], v[64:65]
	v_pk_mul_f32 v[64:65], v[52:53], v[66:67]
	v_pk_mul_f32 v[48:49], v[52:53], v[48:49]
	v_fma_f32 v42, v45, v69, v47
	v_fma_f32 v47, v45, v70, v57
	v_fma_f32 v52, v45, v71, v61
	v_fma_f32 v51, v45, v72, v51
	v_fma_f32 v53, v45, v73, v55
	v_fma_f32 v55, v45, v74, v63
	v_fma_f32 v57, v45, v75, v65
	v_fma_f32 v45, v45, v76, v49
	v_add_f32_e32 v42, v46, v42
	v_add_f32_e32 v46, v56, v47
	v_add_f32_e32 v47, v60, v52
	v_add_f32_e32 v49, v50, v51
	v_add_f32_e32 v50, v54, v53
	v_add_f32_e32 v51, v62, v55
	v_add_f32_e32 v52, v64, v57
	v_add_f32_e32 v45, v48, v45
	v_cvt_pk_bf16_f32 v46, v42, v46
	v_cvt_pk_bf16_f32 v47, v47, v49
	v_cvt_pk_bf16_f32 v48, v50, v51
	v_cvt_pk_bf16_f32 v49, v52, v45
	global_store_dwordx4 v[58:59], v[46:49], off
	s_mov_b64 exec, s[98:99]
	s_andn2_b64 exec, exec, s[6:7]
	s_cbranch_execnz .LBB0_1083

	.amdhsa_kernel _Z6mk_fwd4Args
		.amdhsa_group_segment_fixed_size 0
		.amdhsa_private_segment_fixed_size 0
		.amdhsa_kernarg_size 432
		.amdhsa_user_sgpr_count 2
		.amdhsa_user_sgpr_dispatch_ptr 0
		.amdhsa_user_sgpr_queue_ptr 0
		.amdhsa_user_sgpr_kernarg_segment_ptr 1
		.amdhsa_user_sgpr_dispatch_id 0
		.amdhsa_user_sgpr_kernarg_preload_length 0
		.amdhsa_user_sgpr_kernarg_preload_offset 0
		.amdhsa_user_sgpr_private_segment_size 0
		.amdhsa_uses_dynamic_stack 0
		.amdhsa_enable_private_segment 0
		.amdhsa_system_sgpr_workgroup_id_x 1
		.amdhsa_system_sgpr_workgroup_id_y 0
		.amdhsa_system_sgpr_workgroup_id_z 0
		.amdhsa_system_sgpr_workgroup_info 0
		.amdhsa_system_vgpr_workitem_id 0
		.amdhsa_next_free_vgpr 223
		.amdhsa_next_free_sgpr 102
		.amdhsa_accum_offset 224
		.amdhsa_reserve_vcc 1
		.amdhsa_float_round_mode_32 0
		.amdhsa_float_round_mode_16_64 0
		.amdhsa_float_denorm_mode_32 3
		.amdhsa_float_denorm_mode_16_64 3
		.amdhsa_dx10_clamp 1
		.amdhsa_ieee_mode 1
		.amdhsa_fp16_overflow 0
		.amdhsa_tg_split 0
		.amdhsa_exception_fp_ieee_invalid_op 0
		.amdhsa_exception_fp_denorm_src 0
		.amdhsa_exception_fp_ieee_div_zero 0
		.amdhsa_exception_fp_ieee_overflow 0
		.amdhsa_exception_fp_ieee_underflow 0
		.amdhsa_exception_fp_ieee_inexact 0
		.amdhsa_exception_int_div_zero 0
	.end_amdhsa_kernel

amdhsa.kernels:
  - .agpr_count:     0
    .args:
      - .offset:         0
        .size:           176
        .value_kind:     by_value
      - .offset:         176
        .size:           4
        .value_kind:     hidden_block_count_x
      - .offset:         180
        .size:           4
        .value_kind:     hidden_block_count_y
      - .offset:         184
        .size:           4
        .value_kind:     hidden_block_count_z
      - .offset:         188
        .size:           2
        .value_kind:     hidden_group_size_x
      - .offset:         190
        .size:           2
        .value_kind:     hidden_group_size_y
      - .offset:         192
        .size:           2
        .value_kind:     hidden_group_size_z
      - .offset:         194
        .size:           2
        .value_kind:     hidden_remainder_x
      - .offset:         196
        .size:           2
        .value_kind:     hidden_remainder_y
      - .offset:         198
        .size:           2
        .value_kind:     hidden_remainder_z
      - .offset:         216
        .size:           8
        .value_kind:     hidden_global_offset_x
      - .offset:         224
        .size:           8
        .value_kind:     hidden_global_offset_y
      - .offset:         232
        .size:           8
        .value_kind:     hidden_global_offset_z
      - .offset:         240
        .size:           2
        .value_kind:     hidden_grid_dims
      - .offset:         296
        .size:           4
        .value_kind:     hidden_dynamic_lds_size
    .group_segment_fixed_size: 0
    .kernarg_segment_align: 8
    .kernarg_segment_size: 432
    .language:       OpenCL C
    .language_version:
      - 2
      - 0
    .max_flat_workgroup_size: 512
    .name:           _Z6mk_fwd4Args
    .private_segment_fixed_size: 0
    .sgpr_count:     108
    .sgpr_spill_count: 145
    .symbol:         _Z6mk_fwd4Args.kd
    .uniform_work_group_size: 1
    .uses_dynamic_stack: false
    .vgpr_count:     223
    .vgpr_spill_count: 0
    .wavefront_size: 64
